# diff-attn loop restructure: next-tile K fragments prefetched in PV MFMA shadows, V reads first in PV segment, row-sum adds moved to softmax segment, row-max skipped for tiles j>0 behind an overflow gu
# speedup vs baseline: 1.0248x; 1.0248x over previous
; __device__ __forceinline__ int crow(int r, int hi) { return (r & 3) + 8 * (r >> 2) + 4 * hi; }
; __device__ __forceinline__ void na_unit(const bf16_t* __restrict__ proj, bf16_t* __restrict__ mix, const float* __restrict__ rpb,
;                                         int rowbase, int ROWS, int h, int rg, char* lds, int widk) {
;     ...
;             const char* Ks = K_lds + b * SHM_K;
; #pragma unroll
;             for (int d0 = 0; d0 < 8; ++d0) { const int cb = (d0 * 16 + hi * 8) * 2;
;                 const bf16x8 b0 = *(const bf16x8*)(Ks + KSWZ128(r32, cb)); const bf16x8 b1 = *(const bf16x8*)(Ks + KSWZ128(32 + r32, cb));
;                 p0 = __builtin_amdgcn_mfma_f32_32x32x16_bf16(b0, qr[d0], p0, 0, 0, 0); p1 = __builtin_amdgcn_mfma_f32_32x32x16_bf16(b1, qr[d0], p1, 0, 0, 0); }
;             const float* brow = rpbL + (kr - rq + 7) * 31;
; #pragma unroll
;             for (int r = 0; r < 16; ++r) {
;                 const int kc = crow(r, hi), kc2 = kc + 32;
;                 const int i0 = min(max(kc - c + 15, 0), 30), i1 = min(max(kc2 - c + 15, 0), 30);
;                 const float b0 = brow[i0], b1 = brow[i1];
;                 p0[r] = ((unsigned)(kc - cs) < 16u) ? p0[r] + b0 : -1e30f;
;                 p1[r] = ((unsigned)(kc2 - cs) < 16u) ? p1[r] + b1 : -1e30f;
;             }
.LBB0_320:
	v_cmp_ge_u32_e32 vcc, s84, v151
	v_cmp_lt_u32_e64 s[72:73], s84, v152
	s_and_b64 vcc, vcc, s[72:73]
	s_and_saveexec_b64 s[72:73], vcc
	s_cbranch_execz .LBB0_358
	s_lshl_b32 s84, s85, 14
	v_add_u32_e32 v202, s84, v153
	v_add_u32_e32 v70, v202, v154
	ds_read_b128 v[66:69], v70 offset:32768
	v_add_u32_e32 v203, v202, v155
	ds_read_b128 v[198:201], v203 offset:32768
	s_waitcnt lgkmcnt(0)
	v_mfma_f32_32x32x16_bf16 v[82:97], v[66:69], v[98:101], 0
	ds_read_b128 v[66:69], v70 offset:40960
	v_mfma_f32_32x32x16_bf16 v[82:97], v[198:201], v[102:105], v[82:97]
	ds_read_b128 v[198:201], v203 offset:40960
	v_add_u32_e32 v203, v202, v156
	s_waitcnt lgkmcnt(0)
	v_mfma_f32_32x32x16_bf16 v[66:81], v[66:69], v[98:101], 0
	v_mfma_f32_32x32x16_bf16 v[66:81], v[198:201], v[102:105], v[66:81]
	ds_read_b128 v[198:201], v203 offset:32768
	s_waitcnt lgkmcnt(0)
	v_mfma_f32_32x32x16_bf16 v[82:97], v[198:201], v[106:109], v[82:97]
	ds_read_b128 v[198:201], v203 offset:40960
	v_add_u32_e32 v203, v202, v157
	s_waitcnt lgkmcnt(0)
	v_mfma_f32_32x32x16_bf16 v[66:81], v[198:201], v[106:109], v[66:81]
	ds_read_b128 v[198:201], v203 offset:32768
	s_waitcnt lgkmcnt(0)
	v_mfma_f32_32x32x16_bf16 v[82:97], v[198:201], v[110:113], v[82:97]
	ds_read_b128 v[198:201], v203 offset:40960
	v_add_u32_e32 v203, v202, v158
	s_waitcnt lgkmcnt(0)
	v_mfma_f32_32x32x16_bf16 v[66:81], v[198:201], v[110:113], v[66:81]
	ds_read_b128 v[198:201], v203 offset:32768
	s_waitcnt lgkmcnt(0)
	v_mfma_f32_32x32x16_bf16 v[82:97], v[198:201], v[114:117], v[82:97]
	ds_read_b128 v[198:201], v203 offset:40960
	v_add_u32_e32 v203, v202, v159
	s_waitcnt lgkmcnt(0)
	v_mfma_f32_32x32x16_bf16 v[66:81], v[198:201], v[114:117], v[66:81]
	ds_read_b128 v[198:201], v203 offset:32768
	s_waitcnt lgkmcnt(0)
	v_mfma_f32_32x32x16_bf16 v[82:97], v[198:201], v[118:121], v[82:97]
	ds_read_b128 v[198:201], v203 offset:40960
	v_add_u32_e32 v203, v202, v160
	v_add_u32_e32 v202, v202, v161
	s_waitcnt lgkmcnt(0)
	v_mfma_f32_32x32x16_bf16 v[66:81], v[198:201], v[118:121], v[66:81]
	ds_read_b128 v[198:201], v203 offset:32768
	s_waitcnt lgkmcnt(0)
	v_mfma_f32_32x32x16_bf16 v[82:97], v[198:201], v[122:125], v[82:97]
	ds_read_b128 v[198:201], v203 offset:40960
	s_waitcnt lgkmcnt(0)
	v_mfma_f32_32x32x16_bf16 v[66:81], v[198:201], v[122:125], v[66:81]
	ds_read_b128 v[198:201], v202 offset:32768
	ds_read_b128 v[202:205], v202 offset:40960
	s_waitcnt lgkmcnt(0)
	v_mfma_f32_32x32x16_bf16 v[82:97], v[198:201], v[126:129], v[82:97]
	v_add_u32_e32 v198, v164, v195
	ds_read_b32 v201, v198
	v_mov_b32_e32 v198, 0xf149f2ca
	v_mov_b32_e32 v199, 0xf149f2ca
	v_mfma_f32_32x32x16_bf16 v[66:81], v[202:205], v[126:129], v[66:81]
	s_and_saveexec_b64 vcc, s[6:7]
	s_cbranch_execz .LBB0_323
	v_add_u32_e32 v199, v164, v194
	ds_read_b32 v199, v199
	s_waitcnt lgkmcnt(0)
	s_nop 1
	v_add_f32_e32 v199, v82, v199
.LBB0_323:
	s_or_b64 exec, exec, vcc
	s_nop 3
	v_add_u32_e32 v82, v164, v193
	ds_read_b32 v82, v82
	s_and_saveexec_b64 vcc, s[10:11]
	s_cbranch_execz .LBB0_325
	v_add_u32_e32 v198, v164, v192
	ds_read_b32 v198, v198
	s_waitcnt lgkmcnt(0)
	v_add_f32_e32 v198, v83, v198
.LBB0_325:
	s_or_b64 exec, exec, vcc
	v_add_u32_e32 v83, v164, v191
	ds_read_b32 v202, v83
	v_mov_b32_e32 v83, 0xf149f2ca
	v_mov_b32_e32 v200, 0xf149f2ca
	s_and_saveexec_b64 vcc, s[14:15]
	s_cbranch_execz .LBB0_327
	v_add_u32_e32 v200, v164, v190
	ds_read_b32 v200, v200
	s_waitcnt lgkmcnt(0)
	v_add_f32_e32 v200, v84, v200
.LBB0_327:
	s_or_b64 exec, exec, vcc
	v_add_u32_e32 v84, v164, v189
	ds_read_b32 v203, v84
	s_and_saveexec_b64 vcc, s[18:19]
	s_cbranch_execz .LBB0_329
	v_add_u32_e32 v83, v164, v188
	ds_read_b32 v83, v83
	s_waitcnt lgkmcnt(0)
	v_add_f32_e32 v83, v85, v83
.LBB0_329:
	s_or_b64 exec, exec, vcc
	v_add_u32_e32 v84, v164, v187
	ds_read_b32 v204, v84
	v_mov_b32_e32 v84, 0xf149f2ca
	v_mov_b32_e32 v85, 0xf149f2ca
	s_and_saveexec_b64 vcc, s[22:23]
	s_cbranch_execz .LBB0_331
	v_add_u32_e32 v85, v164, v186
	ds_read_b32 v85, v85
	s_waitcnt lgkmcnt(0)
	v_add_f32_e32 v85, v86, v85
.LBB0_331:
	s_or_b64 exec, exec, vcc
	v_add_u32_e32 v86, v164, v185
	ds_read_b32 v205, v86
	s_and_saveexec_b64 vcc, s[26:27]
	s_cbranch_execz .LBB0_333
	v_add_u32_e32 v84, v164, v184
	ds_read_b32 v84, v84
	s_waitcnt lgkmcnt(0)
	v_add_f32_e32 v84, v87, v84
.LBB0_333:
	s_or_b64 exec, exec, vcc
	v_add_u32_e32 v86, v164, v183
	ds_read_b32 v206, v86
	v_mov_b32_e32 v86, 0xf149f2ca
	v_mov_b32_e32 v87, 0xf149f2ca
	s_and_saveexec_b64 vcc, s[30:31]
	s_cbranch_execz .LBB0_335
	v_add_u32_e32 v87, v164, v182
	ds_read_b32 v87, v87
	s_waitcnt lgkmcnt(0)
	v_add_f32_e32 v87, v88, v87
.LBB0_335:
	s_or_b64 exec, exec, vcc
	v_add_u32_e32 v88, v164, v181
	ds_read_b32 v207, v88
	s_and_saveexec_b64 vcc, s[36:37]
	s_cbranch_execz .LBB0_337
	v_add_u32_e32 v86, v164, v180
	ds_read_b32 v86, v86
	s_waitcnt lgkmcnt(0)
	v_add_f32_e32 v86, v89, v86
.LBB0_337:
	s_or_b64 exec, exec, vcc
	v_add_u32_e32 v88, v164, v179
	ds_read_b32 v208, v88
	v_mov_b32_e32 v88, 0xf149f2ca
	v_mov_b32_e32 v89, 0xf149f2ca
	s_and_saveexec_b64 vcc, s[40:41]
	s_cbranch_execz .LBB0_339
	v_add_u32_e32 v89, v164, v178
	ds_read_b32 v89, v89
	s_waitcnt lgkmcnt(0)
	v_add_f32_e32 v89, v90, v89
.LBB0_339:
	s_or_b64 exec, exec, vcc
	v_add_u32_e32 v90, v164, v177
	ds_read_b32 v209, v90
	s_and_saveexec_b64 vcc, s[44:45]
	s_cbranch_execz .LBB0_341
	v_add_u32_e32 v88, v164, v176
	ds_read_b32 v88, v88
	s_waitcnt lgkmcnt(0)
	v_add_f32_e32 v88, v91, v88
.LBB0_341:
	s_or_b64 exec, exec, vcc
	v_add_u32_e32 v90, v164, v175
	ds_read_b32 v210, v90
	v_mov_b32_e32 v90, 0xf149f2ca
	v_mov_b32_e32 v91, 0xf149f2ca
	s_and_saveexec_b64 vcc, s[48:49]
	s_cbranch_execz .LBB0_343
	v_add_u32_e32 v91, v164, v174
	ds_read_b32 v91, v91
	s_waitcnt lgkmcnt(0)
	v_add_f32_e32 v91, v92, v91
; __device__ __forceinline__ int crow(int r, int hi) { return (r & 3) + 8 * (r >> 2) + 4 * hi; }
; __device__ __forceinline__ void softmax_tile(f32x16& p0, f32x16& p1, float& m_reg, float& l_reg, float& alpha, bf16x8& pa0, bf16x8& pa1, bf16x8& pa2, bf16x8& pa3) {
;     float pmax = p0[0];
; #pragma unroll
;     for (int r = 1; r < 16; ++r) pmax = fmaxf(pmax, p0[r]);
; #pragma unroll
;     for (int r = 0; r < 16; ++r) pmax = fmaxf(pmax, p1[r]);
;     { auto rr = __builtin_amdgcn_permlane32_swap(__float_as_uint(pmax), __float_as_uint(pmax), false, false); pmax = fmaxf(__uint_as_float(rr[0]), __uint_as_float(rr[1])); }
;     float mn;
;     if (__builtin_expect(__all(pmax - m_reg <= THR), 1)) { mn = m_reg; alpha = 1.f; }
;     else { mn = fmaxf(m_reg, pmax); alpha = __builtin_amdgcn_exp2f(m_reg - mn); m_reg = mn; }
; __device__ __forceinline__ void na_unit(const bf16_t* __restrict__ proj, bf16_t* __restrict__ mix, const float* __restrict__ rpb,
;                                         int rowbase, int ROWS, int h, int rg, char* lds, int widk) {
;     ...
;             for (int r = 0; r < 16; ++r) {
;                 const int kc = crow(r, hi), kc2 = kc + 32;
;                 const int i0 = min(max(kc - c + 15, 0), 30), i1 = min(max(kc2 - c + 15, 0), 30);
;                 const float b0 = brow[i0], b1 = brow[i1];
;                 p0[r] = ((unsigned)(kc - cs) < 16u) ? p0[r] + b0 : -1e30f;
;                 p1[r] = ((unsigned)(kc2 - cs) < 16u) ? p1[r] + b1 : -1e30f;
;             }
.LBB0_343:
	s_or_b64 exec, exec, vcc
	v_add_u32_e32 v92, v164, v173
	ds_read_b32 v211, v92
	s_and_saveexec_b64 vcc, s[52:53]
	s_cbranch_execz .LBB0_345
	v_add_u32_e32 v90, v164, v172
	ds_read_b32 v90, v90
	s_waitcnt lgkmcnt(0)
	v_add_f32_e32 v90, v93, v90
.LBB0_345:
	s_or_b64 exec, exec, vcc
	v_add_u32_e32 v92, v164, v171
	ds_read_b32 v212, v92
	v_mov_b32_e32 v92, 0xf149f2ca
	v_mov_b32_e32 v93, 0xf149f2ca
	s_and_saveexec_b64 vcc, s[56:57]
	s_cbranch_execz .LBB0_347
	v_add_u32_e32 v93, v164, v170
	ds_read_b32 v93, v93
	s_waitcnt lgkmcnt(0)
	v_add_f32_e32 v93, v94, v93
.LBB0_347:
	s_or_b64 exec, exec, vcc
	v_add_u32_e32 v94, v164, v169
	ds_read_b32 v213, v94
	s_and_saveexec_b64 vcc, s[60:61]
	s_cbranch_execz .LBB0_349
	v_add_u32_e32 v92, v164, v168
	ds_read_b32 v92, v92
	s_waitcnt lgkmcnt(0)
	v_add_f32_e32 v92, v95, v92
.LBB0_349:
	s_or_b64 exec, exec, vcc
	v_add_u32_e32 v94, v164, v167
	ds_read_b32 v214, v94
	v_mov_b32_e32 v94, 0xf149f2ca
	v_mov_b32_e32 v95, 0xf149f2ca
	s_and_saveexec_b64 vcc, s[64:65]
	s_cbranch_execz .LBB0_351
	v_add_u32_e32 v95, v164, v166
	ds_read_b32 v95, v95
	s_waitcnt lgkmcnt(0)
	v_add_f32_e32 v95, v96, v95
.LBB0_351:
	s_or_b64 exec, exec, vcc
	v_add_u32_e32 v96, v164, v165
	ds_read_b32 v96, v96
	s_and_saveexec_b64 vcc, s[68:69]
	s_cbranch_execz .LBB0_353
	v_add_u32_e32 v94, v164, v163
	ds_read_b32 v94, v94
	s_waitcnt lgkmcnt(0)
	v_add_f32_e32 v94, v97, v94
.LBB0_353:
	s_or_b64 exec, exec, vcc
	s_waitcnt lgkmcnt(0)
	v_add_f32_e32 v67, v67, v82
	v_add_f32_e32 v81, v81, v96
	v_max_f32_e32 v82, v198, v198
	v_max_f32_e32 v96, v199, v199
	v_max_f32_e32 v82, v96, v82
	v_max3_f32 v82, v82, v200, v83
	v_max3_f32 v82, v82, v85, v84
	v_max3_f32 v82, v82, v87, v86
	v_max3_f32 v82, v82, v89, v88
	v_max3_f32 v82, v82, v91, v90
	v_add_f32_e32 v66, v66, v201
	v_max3_f32 v82, v82, v93, v92
	v_add_f32_e32 v69, v69, v203
	v_add_f32_e32 v68, v68, v202
	v_cndmask_b32_e64 v67, v141, v67, s[12:13]
	v_cndmask_b32_e64 v66, v141, v66, s[8:9]
	v_max3_f32 v82, v82, v95, v94
	v_add_f32_e32 v71, v71, v205
	v_add_f32_e32 v70, v70, v204
	v_cndmask_b32_e64 v69, v141, v69, s[20:21]
	v_cndmask_b32_e64 v68, v141, v68, s[16:17]
	v_max3_f32 v82, v82, v66, v67
	v_add_f32_e32 v73, v73, v207
	v_add_f32_e32 v72, v72, v206
	v_cndmask_b32_e64 v71, v141, v71, s[28:29]
	v_cndmask_b32_e64 v70, v141, v70, s[24:25]
	v_max3_f32 v82, v82, v68, v69
	v_add_f32_e32 v75, v75, v209
	v_add_f32_e32 v74, v74, v208
	v_cndmask_b32_e64 v73, v141, v73, s[38:39]
	v_cndmask_b32_e64 v72, v141, v72, s[34:35]
	v_max3_f32 v82, v82, v70, v71
	v_add_f32_e32 v77, v77, v211
	v_add_f32_e32 v76, v76, v210
	v_cndmask_b32_e64 v75, v141, v75, s[46:47]
	v_cndmask_b32_e64 v74, v141, v74, s[42:43]
	v_max3_f32 v82, v82, v72, v73
	v_add_f32_e32 v79, v79, v213
	v_add_f32_e32 v78, v78, v212
	v_cndmask_b32_e64 v77, v141, v77, s[54:55]
	v_cndmask_b32_e64 v76, v141, v76, s[50:51]
	v_max3_f32 v82, v82, v74, v75
	v_add_f32_e32 v80, v80, v214
	v_cndmask_b32_e64 v79, v141, v79, s[62:63]
	v_cndmask_b32_e64 v78, v141, v78, s[58:59]
	v_max3_f32 v82, v82, v76, v77
	v_cndmask_b32_e64 v80, v141, v80, s[66:67]
	v_cndmask_b32_e64 v81, v141, v81, s[70:71]
	v_max3_f32 v82, v82, v78, v79
	v_max3_f32 v82, v82, v80, v81
	v_mov_b32_e32 v96, v82
	s_nop 1
	v_permlane32_swap_b32_e32 v82, v96
	v_max_f32_e32 v96, v96, v96
	v_max_f32_e32 v82, v82, v82
	v_max_f32_e32 v82, v82, v96
	v_sub_f32_e32 v96, v82, v196
	s_mov_b32 s80, 0x41000000
	v_cmp_ge_f32_e32 vcc, s80, v96
	v_max_f32_e32 v97, v196, v196
	s_cmp_eq_u64 vcc, exec
	v_max_f32_e32 v97, v97, v82
	s_cselect_b64 vcc, -1, 0
	v_sub_f32_e32 v82, v196, v97
	v_cndmask_b32_e32 v196, v97, v196, vcc
	v_sub_f32_e32 v96, v199, v196
	v_sub_f32_e32 v66, v66, v196
	v_exp_f32_e32 v96, v96
	v_exp_f32_e32 v97, v66
	v_sub_f32_e32 v66, v198, v196
	v_sub_f32_e32 v67, v67, v196
	v_exp_f32_e32 v66, v66
	v_exp_f32_e32 v198, v67
	v_sub_f32_e32 v67, v200, v196
	v_sub_f32_e32 v68, v68, v196
	v_exp_f32_e32 v67, v67
	v_exp_f32_e32 v199, v68
	v_sub_f32_e32 v68, v83, v196
	v_sub_f32_e32 v69, v69, v196
	v_exp_f32_e32 v68, v68
	v_exp_f32_e32 v200, v69
	v_sub_f32_e32 v69, v85, v196
	v_sub_f32_e32 v70, v70, v196
	v_exp_f32_e32 v69, v69
	v_exp_f32_e32 v85, v70
	v_sub_f32_e32 v70, v84, v196
	v_sub_f32_e32 v71, v71, v196
	v_add_f32_e32 v83, 0, v96
	v_exp_f32_e32 v70, v70
	v_exp_f32_e32 v201, v71
	v_sub_f32_e32 v71, v87, v196
	v_sub_f32_e32 v72, v72, v196
	v_add_f32_e32 v83, v66, v83
	v_exp_f32_e32 v71, v71
	v_exp_f32_e32 v87, v72
	v_sub_f32_e32 v72, v86, v196
	v_sub_f32_e32 v73, v73, v196
; __device__ __forceinline__ void softmax_tile(f32x16& p0, f32x16& p1, float& m_reg, float& l_reg, float& alpha, bf16x8& pa0, bf16x8& pa1, bf16x8& pa2, bf16x8& pa3) {
;     ...
; #pragma unroll
;     for (int r = 0; r < 16; ++r) { p0[r] = __builtin_amdgcn_exp2f(p0[r] - mn); p1[r] = __builtin_amdgcn_exp2f(p1[r] - mn); }
;     float ps = 0.f;
; #pragma unroll
;     for (int r = 0; r < 16; ++r) ps += p0[r];
; #pragma unroll
;     for (int r = 0; r < 16; ++r) ps += p1[r];
;     { auto rr = __builtin_amdgcn_permlane32_swap(__float_as_uint(ps), __float_as_uint(ps), false, false); ps = __uint_as_float(rr[0]) + __uint_as_float(rr[1]); }
;     l_reg = l_reg * alpha + ps;
;     ...
;     PK4(p0, 0, pa0); PK4(p0, 8, pa1); PK4(p1, 0, pa2); PK4(p1, 8, pa3);
	v_add_f32_e32 v83, v67, v83
	v_exp_f32_e32 v72, v72
	v_exp_f32_e32 v86, v73
	v_sub_f32_e32 v73, v89, v196
	v_sub_f32_e32 v74, v74, v196
	v_add_f32_e32 v83, v68, v83
	v_exp_f32_e32 v73, v73
	v_exp_f32_e32 v89, v74
	v_sub_f32_e32 v74, v88, v196
	v_sub_f32_e32 v75, v75, v196
	v_add_f32_e32 v83, v69, v83
	v_exp_f32_e32 v74, v74
	v_exp_f32_e32 v88, v75
	v_sub_f32_e32 v75, v91, v196
	v_sub_f32_e32 v76, v76, v196
	v_add_f32_e32 v83, v70, v83
	v_exp_f32_e32 v75, v75
	v_exp_f32_e32 v91, v76
	v_sub_f32_e32 v76, v90, v196
	v_sub_f32_e32 v77, v77, v196
	v_add_f32_e32 v83, v71, v83
	v_exp_f32_e32 v76, v76
	v_exp_f32_e32 v90, v77
	v_sub_f32_e32 v77, v93, v196
	v_sub_f32_e32 v78, v78, v196
	v_add_f32_e32 v83, v72, v83
	v_exp_f32_e32 v77, v77
	v_exp_f32_e32 v93, v78
	v_sub_f32_e32 v78, v92, v196
	v_sub_f32_e32 v79, v79, v196
	v_add_f32_e32 v83, v73, v83
	v_exp_f32_e32 v78, v78
	v_exp_f32_e32 v92, v79
	v_sub_f32_e32 v79, v95, v196
	v_sub_f32_e32 v80, v80, v196
	v_add_f32_e32 v83, v74, v83
	v_exp_f32_e32 v79, v79
	v_exp_f32_e32 v95, v80
	v_sub_f32_e32 v80, v94, v196
	v_add_f32_e32 v83, v75, v83
	v_exp_f32_e32 v80, v80
	v_add_f32_e32 v83, v76, v83
	v_add_f32_e32 v83, v77, v83
	v_add_f32_e32 v83, v78, v83
	v_add_f32_e32 v83, v79, v83
	v_add_f32_e32 v83, v80, v83
	v_add_f32_e32 v83, v97, v83
	v_add_f32_e32 v83, v198, v83
	v_add_f32_e32 v83, v199, v83
	v_add_f32_e32 v83, v200, v83
	v_add_f32_e32 v83, v85, v83
	v_add_f32_e32 v83, v201, v83
	v_add_f32_e32 v83, v87, v83
	v_add_f32_e32 v83, v86, v83
	v_add_f32_e32 v83, v89, v83
	v_add_f32_e32 v83, v88, v83
	v_sub_f32_e32 v81, v81, v196
	v_add_f32_e32 v83, v91, v83
	v_exp_f32_e32 v81, v81
	v_add_f32_e32 v83, v90, v83
	v_exp_f32_e32 v82, v82
	v_add_f32_e32 v83, v93, v83
	v_add_f32_e32 v83, v92, v83
	v_add_f32_e32 v83, v95, v83
	v_add_f32_e32 v83, v81, v83
	v_cndmask_b32_e64 v82, v82, 1.0, vcc
	v_mov_b32_e32 v84, v83
	v_cvt_pk_bf16_f32 v66, v96, v66
	v_cvt_pk_bf16_f32 v67, v67, v68
	v_cvt_pk_bf16_f32 v68, v69, v70
	v_cvt_pk_bf16_f32 v69, v71, v72
	v_cvt_pk_bf16_f32 v70, v73, v74
	v_cvt_pk_bf16_f32 v71, v75, v76
	v_cvt_pk_bf16_f32 v72, v77, v78
	v_cvt_pk_bf16_f32 v73, v79, v80
	v_cvt_pk_bf16_f32 v74, v97, v198
	v_cvt_pk_bf16_f32 v75, v199, v200
	v_cvt_pk_bf16_f32 v76, v85, v201
	v_cvt_pk_bf16_f32 v77, v87, v86
	v_cvt_pk_bf16_f32 v78, v89, v88
	v_cvt_pk_bf16_f32 v79, v91, v90
	v_cvt_pk_bf16_f32 v80, v93, v92
	v_cvt_pk_bf16_f32 v81, v95, v81
	s_nop 1
	v_permlane32_swap_b32_e32 v83, v84
	v_permlane32_swap_b32_e32 v66, v68
	v_permlane32_swap_b32_e32 v67, v69
	v_permlane32_swap_b32_e32 v70, v72
	v_permlane32_swap_b32_e32 v71, v73
	v_permlane32_swap_b32_e32 v74, v76
	v_permlane32_swap_b32_e32 v75, v77
	v_permlane32_swap_b32_e32 v78, v80
	v_permlane32_swap_b32_e32 v79, v81
	v_cmp_gt_f32_e32 vcc, 1.0, v82
	s_cbranch_vccz .LBB0_357
	s_and_saveexec_b64 vcc, s[4:5]
	ds_write_b32 v150, v82 offset:128
	s_or_b64 exec, exec, vcc
	s_waitcnt lgkmcnt(0)
	v_add_u32_e32 v85, v149, v0
	ds_read_b128 v[86:89], v85 offset:224
	ds_read_b128 v[90:93], v85 offset:192
	ds_read_b128 v[94:97], v85 offset:160
	ds_read_b128 v[198:201], v85 offset:128
	s_waitcnt lgkmcnt(0)
	v_pk_mul_f32 v[62:63], v[62:63], v[86:87]
	v_pk_mul_f32 v[58:59], v[58:59], v[90:91]
	v_pk_mul_f32 v[54:55], v[54:55], v[94:95]
	v_pk_mul_f32 v[64:65], v[64:65], v[88:89]
	v_pk_mul_f32 v[60:61], v[60:61], v[92:93]
	v_pk_mul_f32 v[56:57], v[56:57], v[96:97]
	v_pk_mul_f32 v[52:53], v[52:53], v[200:201]
	v_pk_mul_f32 v[50:51], v[50:51], v[198:199]
	v_pk_mul_f32 v[46:47], v[46:47], v[86:87]
	v_pk_mul_f32 v[42:43], v[42:43], v[90:91]
	v_pk_mul_f32 v[38:39], v[38:39], v[94:95]
	v_pk_mul_f32 v[48:49], v[48:49], v[88:89]
	v_pk_mul_f32 v[44:45], v[44:45], v[92:93]
	v_pk_mul_f32 v[40:41], v[40:41], v[96:97]
	v_pk_mul_f32 v[36:37], v[36:37], v[200:201]
	v_pk_mul_f32 v[34:35], v[34:35], v[198:199]
	v_pk_mul_f32 v[30:31], v[30:31], v[86:87]
	v_pk_mul_f32 v[26:27], v[26:27], v[90:91]
	v_pk_mul_f32 v[22:23], v[22:23], v[94:95]
	v_pk_mul_f32 v[32:33], v[32:33], v[88:89]
	v_pk_mul_f32 v[28:29], v[28:29], v[92:93]
	v_pk_mul_f32 v[24:25], v[24:25], v[96:97]
	v_pk_mul_f32 v[20:21], v[20:21], v[200:201]
	v_pk_mul_f32 v[18:19], v[18:19], v[198:199]
	v_pk_mul_f32 v[14:15], v[14:15], v[86:87]
	v_pk_mul_f32 v[10:11], v[10:11], v[90:91]
	v_pk_mul_f32 v[6:7], v[6:7], v[94:95]
	v_pk_mul_f32 v[16:17], v[16:17], v[88:89]
	v_pk_mul_f32 v[12:13], v[12:13], v[92:93]
	v_pk_mul_f32 v[8:9], v[8:9], v[96:97]
	v_pk_mul_f32 v[4:5], v[4:5], v[200:201]
	v_pk_mul_f32 v[2:3], v[2:3], v[198:199]

; #define SBAR() __builtin_amdgcn_sched_barrier(0)
; __device__ __forceinline__ void diff_unit(const bf16_t* __restrict__ proj, bf16_t* __restrict__ mix, float* __restrict__ o1s, const float* __restrict__ g_sub, float lam,
;                                           int rowbase, int T, int h, int qb, char* lds, int widk) {
;     ...
;         float m_reg = 0.f, l_reg = 0.f; f32x16 o[4], negm = f32x16{};
; #pragma unroll
;         for (int d = 0; d < 4; ++d) o[d] = f32x16{};
;     ...
; #pragma unroll
;         for (int t = 0; t < DF_D; ++t) DDMA(t, t);
;         asm volatile("s_waitcnt vmcnt(%0)" :: "n"(3 * (DF_D - 1)) : "memory"); BAR();
;         int ka[4];
; #pragma unroll
;         for (int d0 = 0; d0 < 4; ++d0) ka[d0] = (int)(uintptr_t)K_lds + KSWZ64(r32, (d0 * 16 + hi * 8) * 2);
;     ...
;         if (grp) BAR();
;         int bsl = 0;
; #pragma unroll 1
;         for (int j = 0; j < NT; ++j) {
;             BAR();
;             f32x16 p0, p1;
;             __builtin_amdgcn_s_setprio(1);
;             { const int kb = bsl * DF_KSZ; bf16x8 k0, k1, k2, k3, k4, k5, k6, k7; const int a0 = ka[0] + kb, a1 = ka[1] + kb, a2 = ka[2] + kb, a3 = ka[3] + kb;
;               KRD(k0, a0, 0); KRD(k1, a0, 4096); KRD(k2, a1, 0); KRD(k3, a1, 4096); KRD(k4, a2, 0); KRD(k5, a2, 4096); KRD(k6, a3, 0); KRD(k7, a3, 4096);
;               asm volatile("s_waitcnt lgkmcnt(6)" ::: "memory"); SBAR();
;               asm volatile("v_mfma_f32_32x32x16_bf16 %0, %1, %2, %3" : "=&v"(p0) : "v"(k0), "v"(qr[0]), "v"(negm));
;               asm volatile("v_mfma_f32_32x32x16_bf16 %0, %1, %2, %3" : "=&v"(p1) : "v"(k1), "v"(qr[0]), "v"(negm)); SBAR();
;               asm volatile("s_waitcnt lgkmcnt(4)" ::: "memory"); SBAR();
;               p0 = __builtin_amdgcn_mfma_f32_32x32x16_bf16(k2, qr[1], p0, 0, 0, 0); p1 = __builtin_amdgcn_mfma_f32_32x32x16_bf16(k3, qr[1], p1, 0, 0, 0); SBAR();
;               asm volatile("s_waitcnt lgkmcnt(2)" ::: "memory"); SBAR();
;               p0 = __builtin_amdgcn_mfma_f32_32x32x16_bf16(k4, qr[2], p0, 0, 0, 0); p1 = __builtin_amdgcn_mfma_f32_32x32x16_bf16(k5, qr[2], p1, 0, 0, 0); SBAR();
;               asm volatile("s_waitcnt lgkmcnt(0)" ::: "memory"); SBAR();
;               p0 = __builtin_amdgcn_mfma_f32_32x32x16_bf16(k6, qr[3], p0, 0, 0, 0); p1 = __builtin_amdgcn_mfma_f32_32x32x16_bf16(k7, qr[3], p1, 0, 0, 0); SBAR(); }
.LBB0_374:
	v_mov_b32_e32 v14, v0
	v_mov_b32_e32 v15, v0
	v_mov_b32_e32 v1, v0
	v_mov_b32_e32 v2, v0
	v_mov_b32_e32 v3, v0
	v_mov_b32_e32 v4, v0
	v_mov_b32_e32 v5, v0
	v_mov_b32_e32 v6, v0
	v_mov_b32_e32 v7, v0
	v_mov_b32_e32 v8, v0
	v_mov_b32_e32 v9, v0
	v_mov_b32_e32 v10, v0
	v_mov_b32_e32 v11, v0
	v_mov_b32_e32 v12, v0
	v_mov_b32_e32 v13, v0
	v_mov_b32_e32 v209, 0
	v_mov_b64_e32 v[30:31], v[14:15]
	v_mov_b64_e32 v[46:47], v[14:15]
	v_mov_b64_e32 v[62:63], v[14:15]
	v_mov_b64_e32 v[78:79], v[14:15]
	s_xor_b64 s[46:47], s[0:1], -1
	v_lshl_add_u64 v[188:189], s[8:9], 1, v[182:183]
	s_mov_b32 s33, 0
	s_mov_b64 s[6:7], 0
	v_mov_b64_e32 v[28:29], v[12:13]
	v_mov_b64_e32 v[26:27], v[10:11]
	v_mov_b64_e32 v[24:25], v[8:9]
	v_mov_b64_e32 v[22:23], v[6:7]
	v_mov_b64_e32 v[20:21], v[4:5]
	v_mov_b64_e32 v[18:19], v[2:3]
	v_mov_b64_e32 v[16:17], v[0:1]
	v_mov_b64_e32 v[44:45], v[12:13]
	v_mov_b64_e32 v[42:43], v[10:11]
	v_mov_b64_e32 v[40:41], v[8:9]
	v_mov_b64_e32 v[38:39], v[6:7]
	v_mov_b64_e32 v[36:37], v[4:5]
	v_mov_b64_e32 v[34:35], v[2:3]
	v_mov_b64_e32 v[32:33], v[0:1]
	v_mov_b64_e32 v[60:61], v[12:13]
	v_mov_b64_e32 v[58:59], v[10:11]
	v_mov_b64_e32 v[56:57], v[8:9]
	v_mov_b64_e32 v[54:55], v[6:7]
	v_mov_b64_e32 v[52:53], v[4:5]
	v_mov_b64_e32 v[50:51], v[2:3]
	v_mov_b64_e32 v[48:49], v[0:1]
	s_mov_b32 s8, 0
	v_mov_b32_e32 v210, 0
	v_mov_b64_e32 v[76:77], v[12:13]
	v_mov_b64_e32 v[74:75], v[10:11]
	v_mov_b64_e32 v[72:73], v[8:9]
	v_mov_b64_e32 v[70:71], v[6:7]
	v_mov_b64_e32 v[68:69], v[4:5]
	v_mov_b64_e32 v[66:67], v[2:3]
	v_mov_b64_e32 v[64:65], v[0:1]
	v_mov_b32_e32 v80, 0
	v_mov_b32_e32 v81, v209
	v_mov_b32_e32 v82, v209
	v_mov_b32_e32 v83, v209
	v_mov_b32_e32 v84, v209
	v_mov_b32_e32 v85, v209
	v_mov_b32_e32 v86, v209
	v_mov_b32_e32 v87, v209
	v_mov_b32_e32 v88, v209
	v_mov_b32_e32 v89, v209
	v_mov_b32_e32 v90, v209
	v_mov_b32_e32 v91, v209
	v_mov_b32_e32 v92, v209
	v_mov_b32_e32 v93, v209
	v_mov_b32_e32 v94, v209
	v_mov_b32_e32 v95, v209
	ds_read_b128 v[236:239], v204
	ds_read_b128 v[240:243], v204 offset:4096
	ds_read_b128 v[244:247], v205
	ds_read_b128 v[248:251], v205 offset:4096
	ds_read_b128 v[216:219], v206
	ds_read_b128 v[220:223], v206 offset:4096
	ds_read_b128 v[224:227], v207
	ds_read_b128 v[228:231], v207 offset:4096
	s_waitcnt vmcnt(0)
.LBB0_375:
	s_barrier
	s_setprio 1
	s_waitcnt lgkmcnt(6)
	v_mfma_f32_32x32x16_bf16 v[112:127], v[236:239], v[128:131], v[80:95]
	v_mfma_f32_32x32x16_bf16 v[96:111], v[240:243], v[128:131], v[80:95]
	s_waitcnt lgkmcnt(4)
	s_nop 0
	v_mfma_f32_32x32x16_bf16 v[112:127], v[244:247], v[132:135], v[112:127]
	v_mfma_f32_32x32x16_bf16 v[96:111], v[248:251], v[132:135], v[96:111]
	s_waitcnt lgkmcnt(2)
	v_mfma_f32_32x32x16_bf16 v[112:127], v[216:219], v[136:139], v[112:127]
	v_mfma_f32_32x32x16_bf16 v[96:111], v[220:223], v[136:139], v[96:111]
	s_waitcnt lgkmcnt(0)
	v_mfma_f32_32x32x16_bf16 v[112:127], v[224:227], v[140:143], v[112:127]
	v_mfma_f32_32x32x16_bf16 v[96:111], v[228:231], v[140:143], v[96:111]
	s_setprio 0
	s_nop 10
	s_mov_b32 s99, 1
	s_cmp_lg_u32 s6, 0
	v_mov_b32_e32 v1, 1.0
	s_cbranch_scc1 .LBB0_380
.Ldf_slow:
	s_mov_b32 s99, 0
	v_max_f32_e32 v3, v97, v97
	v_max_f32_e32 v4, v96, v96
	v_max3_f32 v1, v112, v113, v114
	v_max3_f32 v2, v120, v121, v122
	v_max_f32_e32 v3, v4, v3
	v_max3_f32 v4, v104, v105, v106
	v_max3_f32 v1, v1, v115, v116
	v_max3_f32 v2, v2, v123, v124
	v_max3_f32 v3, v3, v98, v99
	v_max3_f32 v4, v4, v107, v108
	v_max3_f32 v1, v1, v117, v118
	v_max3_f32 v2, v2, v125, v126
	v_max3_f32 v3, v3, v100, v101
	v_max3_f32 v4, v4, v109, v110
	v_max3_f32 v1, v1, v119, v2
	v_max3_f32 v2, v3, v102, v103
	v_max3_f32 v2, v2, v4, v111
	v_max3_f32 v1, v1, v127, v2
	v_mov_b32_e32 v2, v1
	s_nop 1
	v_permlane32_swap_b32_e32 v1, v2
	s_cmp_eq_u32 s6, 0
	v_max_f32_e32 v2, v2, v2
	v_max_f32_e32 v1, v1, v1
	s_cselect_b64 s[0:1], -1, 0
	s_cmp_lg_u32 s6, 0
	v_max_f32_e32 v1, v1, v2
	s_cbranch_scc0 .LBB0_392
	v_cmp_ge_f32_e32 vcc, s63, v1
	s_cmp_lg_u64 vcc, exec
	s_mov_b64 s[50:51], 0
	s_mov_b64 s[48:49], 0
	s_cbranch_scc1 .LBB0_393
	s_and_b64 vcc, exec, s[50:51]
	s_cbranch_vccnz .LBB0_394

; #define BAR() do { asm volatile("" ::: "memory"); __builtin_amdgcn_s_barrier(); asm volatile("" ::: "memory"); } while (0)
; __device__ __forceinline__ void softmax_rel(f32x16& p0, f32x16& p1, float& m_reg, float& l_reg, f32x16& negm, float& alpha, bool first, bf16x8& pa0, bf16x8& pa1, bf16x8& pa2, bf16x8& pa3) {
;     ...
;     float ps0 = p0[0], ps1 = p1[0], ps2 = p0[8], ps3 = p1[8];
; #pragma unroll
;     for (int r = 1; r < 8; ++r) { ps0 += p0[r]; ps1 += p1[r]; ps2 += p0[8 + r]; ps3 += p1[8 + r]; }
;     l_reg = l_reg * alpha + ((ps0 + ps1) + (ps2 + ps3));
; __device__ __forceinline__ void diff_unit(const bf16_t* __restrict__ proj, bf16_t* __restrict__ mix, float* __restrict__ o1s, const float* __restrict__ g_sub, float lam,
;                                           int rowbase, int T, int h, int qb, char* lds, int widk) {
;     ...
;             if (j + DF_D <= NT) asm volatile("s_waitcnt vmcnt(%0) lgkmcnt(0)" :: "n"(3 * (DF_D - 2)) : "memory"); else asm volatile("s_waitcnt vmcnt(0) lgkmcnt(0)" ::: "memory");
;             BAR();
;             if (j + DF_D < NT) { const int b2 = bsl >= 1 ? bsl - 1 : DF_R - 1; DDMA(j + DF_D, b2); }
.LBB0_384:
	v_add_f32_e32 v109, v217, v213
	v_add_f32_e32 v110, v218, v215
	v_add_f32_e32 v111, v220, v119
	v_add_f32_e32 v119, v221, v219
	v_add_f32_e32 v109, v214, v109
	v_add_f32_e32 v110, v216, v110
	v_add_f32_e32 v111, v120, v111
	v_add_f32_e32 v119, v121, v119
	v_add_f32_e32 v109, v211, v109
	v_add_f32_e32 v110, v212, v110
	v_add_f32_e32 v111, v117, v111
	v_add_f32_e32 v117, v118, v119
	v_add_f32_e32 v109, v114, v109
	v_add_f32_e32 v110, v115, v110
	v_add_f32_e32 v111, v116, v111
	v_add_f32_e32 v108, v108, v117
	v_add_f32_e32 v109, v112, v109
	v_add_f32_e32 v110, v113, v110
	v_add_f32_e32 v106, v106, v111
	v_add_f32_e32 v107, v107, v108
	v_add_f32_e32 v100, v100, v109
	v_add_f32_e32 v101, v101, v110
	v_add_f32_e32 v104, v104, v106
	v_add_f32_e32 v105, v105, v107
	v_add_f32_e32 v14, v14, v100
	v_add_f32_e32 v15, v15, v101
	v_add_f32_e32 v100, v102, v104
	v_add_f32_e32 v101, v103, v105
	v_add_f32_e32 v14, v15, v14
	v_add_f32_e32 v15, v101, v100
	v_add_f32_e32 v14, v15, v14
	s_cmp_eq_u32 s99, 0
	s_cbranch_scc1 .Ldf_guard_ok
	v_cmp_gt_f32_e32 vcc, 0x71800000, v14
	s_cmp_lg_u64 vcc, exec
	s_cbranch_scc1 .Ldf_fallback
.Ldf_guard_ok:
	v_fmac_f32_e32 v14, v210, v1
	s_add_i32 s48, s8, 4
	s_cmp_gt_u32 s48, s66
	s_mov_b64 s[0:1], -1
	s_cbranch_scc1 .LBB0_386
	s_waitcnt vmcnt(3) lgkmcnt(0)
	s_mov_b64 s[0:1], 0

; #define SBAR() __builtin_amdgcn_sched_barrier(0)
; #define PV_MMA(od, L, H) do { od = __builtin_amdgcn_mfma_f32_32x32x16_bf16(pa0, PV_PK(L[0], H[0]), od, 0, 0, 0); od = __builtin_amdgcn_mfma_f32_32x32x16_bf16(pa1, PV_PK(L[1], H[1]), od, 0, 0, 0); \
;     od = __builtin_amdgcn_mfma_f32_32x32x16_bf16(pa2, PV_PK(L[2], H[2]), od, 0, 0, 0); od = __builtin_amdgcn_mfma_f32_32x32x16_bf16(pa3, PV_PK(L[3], H[3]), od, 0, 0, 0); } while (0)
; #define BAR() do { asm volatile("" ::: "memory"); __builtin_amdgcn_s_barrier(); asm volatile("" ::: "memory"); } while (0)
; #define KRD(dst, addr, OFF) asm volatile("ds_read_b128 %0, %1 offset:" #OFF : "=&v"(dst) : "v"(addr) : "memory")
; __device__ __forceinline__ void pv_all_pre(f32x16* o, int vb, bf16x8 pa0, bf16x8 pa1, bf16x8 pa2, bf16x8 pa3) {
;     s16x4 L0[4], H0[4], L1[4], H1[4], L2[4], H2[4], L3[4], H3[4];
;     pv_rd<0>(L0, H0, vb); pv_rd<1>(L1, H1, vb);
;     asm volatile("s_waitcnt lgkmcnt(8)" ::: "memory"); SBAR(); PV_MMA(o[0], L0, H0); SBAR();
;     pv_rd<2>(L2, H2, vb);
;     asm volatile("s_waitcnt lgkmcnt(8)" ::: "memory"); SBAR(); PV_MMA(o[1], L1, H1); SBAR();
;     pv_rd<3>(L3, H3, vb);
;     asm volatile("s_waitcnt lgkmcnt(8)" ::: "memory"); SBAR(); PV_MMA(o[2], L2, H2); SBAR();
;     asm volatile("s_waitcnt lgkmcnt(0)" ::: "memory"); SBAR(); PV_MMA(o[3], L3, H3); SBAR();
; __device__ __forceinline__ void diff_unit(const bf16_t* __restrict__ proj, bf16_t* __restrict__ mix, float* __restrict__ o1s, const float* __restrict__ g_sub, float lam,
;                                           int rowbase, int T, int h, int qb, char* lds, int widk) {
;     ...
;             { const int kb = bsl * DF_KSZ; bf16x8 k0, k1, k2, k3, k4, k5, k6, k7; const int a0 = ka[0] + kb, a1 = ka[1] + kb, a2 = ka[2] + kb, a3 = ka[3] + kb;
;               KRD(k0, a0, 0); KRD(k1, a0, 4096); KRD(k2, a1, 0); KRD(k3, a1, 4096); KRD(k4, a2, 0); KRD(k5, a2, 4096); KRD(k6, a3, 0); KRD(k7, a3, 4096);
;     ...
;             if (j + DF_D <= NT) asm volatile("s_waitcnt vmcnt(%0) lgkmcnt(0)" :: "n"(3 * (DF_D - 2)) : "memory"); else asm volatile("s_waitcnt vmcnt(0) lgkmcnt(0)" ::: "memory");
;             BAR();
;             if (j + DF_D < NT) { const int b2 = bsl >= 1 ? bsl - 1 : DF_R - 1; DDMA(j + DF_D, b2); }
;             const int bn = bsl == DF_R - 1 ? 0 : bsl + 1;
;             pv_all_pre(o, vb0 + bsl * SHM_V, pa0, pa1, pa2, pa3);
;             bsl = bn;
.LBB0_388:
	s_barrier
	v_lshl_add_u32 v1, s33, 14, v208
	ds_read_b64_tr_b16 v[100:101], v1 offset:0
	ds_read_b64_tr_b16 v[102:103], v1 offset:0x800
	ds_read_b64_tr_b16 v[104:105], v1 offset:0x1000
	ds_read_b64_tr_b16 v[106:107], v1 offset:0x1800
	ds_read_b64_tr_b16 v[108:109], v1 offset:0x2000
	ds_read_b64_tr_b16 v[110:111], v1 offset:0x2800
	ds_read_b64_tr_b16 v[112:113], v1 offset:0x3000
	ds_read_b64_tr_b16 v[114:115], v1 offset:0x3800
	ds_read_b64_tr_b16 v[116:117], v1 offset:0x200
	ds_read_b64_tr_b16 v[118:119], v1 offset:0xa00
	ds_read_b64_tr_b16 v[120:121], v1 offset:0x1200
	ds_read_b64_tr_b16 v[122:123], v1 offset:0x1a00
	ds_read_b64_tr_b16 v[124:125], v1 offset:0x2200
	ds_read_b64_tr_b16 v[126:127], v1 offset:0x2a00
	ds_read_b64_tr_b16 v[210:211], v1 offset:0x3200
	ds_read_b64_tr_b16 v[212:213], v1 offset:0x3a00
	s_add_i32 s0, s33, 1
	s_cmp_lg_u32 s33, 4
	s_cselect_b32 s0, s0, 0
	s_cmp_ge_u32 s48, s66
	s_cbranch_scc1 .Ldf_skip_dma
	s_add_i32 s98, s33, -1
	s_cmp_gt_i32 s33, 0
	s_cselect_b32 s98, s98, 4
	s_lshl_b32 s99, s98, 13
	s_lshl_b32 s98, s98, 14
	v_lshl_add_u64 v[254:255], v[188:189], 0, s[6:7]
	s_add_i32 m0, s68, s99
	s_add_i32 s98, s67, s98
	global_load_lds_dwordx4 v[254:255], off
	v_lshl_add_u64 v[254:255], v[184:185], 0, s[6:7]
	s_mov_b32 m0, s98
	s_nop 0
	global_load_lds_dwordx4 v[254:255], off
	v_lshl_add_u64 v[254:255], v[186:187], 0, s[6:7]
	s_add_i32 m0, s98, 0x2000
	s_nop 0
	global_load_lds_dwordx4 v[254:255], off
.Ldf_skip_dma:
	s_waitcnt lgkmcnt(8)
	v_mfma_f32_32x32x16_bf16 v[64:79], v[96:99], v[100:103], v[64:79]
	v_mfma_f32_32x32x16_bf16 v[64:79], v[10:13], v[104:107], v[64:79]
	v_mfma_f32_32x32x16_bf16 v[64:79], v[6:9], v[108:111], v[64:79]
	v_mfma_f32_32x32x16_bf16 v[64:79], v[2:5], v[112:115], v[64:79]
	ds_read_b64_tr_b16 v[100:101], v1 offset:0x400
	ds_read_b64_tr_b16 v[102:103], v1 offset:0xc00
	ds_read_b64_tr_b16 v[104:105], v1 offset:0x1400
	ds_read_b64_tr_b16 v[106:107], v1 offset:0x1c00
	ds_read_b64_tr_b16 v[108:109], v1 offset:0x2400
	ds_read_b64_tr_b16 v[110:111], v1 offset:0x2c00
	ds_read_b64_tr_b16 v[112:113], v1 offset:0x3400
	ds_read_b64_tr_b16 v[114:115], v1 offset:0x3c00
	s_waitcnt lgkmcnt(8)
	v_mfma_f32_32x32x16_bf16 v[48:63], v[96:99], v[116:119], v[48:63]
	v_mfma_f32_32x32x16_bf16 v[48:63], v[10:13], v[120:123], v[48:63]
	v_mfma_f32_32x32x16_bf16 v[48:63], v[6:9], v[124:127], v[48:63]
	v_mfma_f32_32x32x16_bf16 v[48:63], v[2:5], v[210:213], v[48:63]
	ds_read_b64_tr_b16 v[116:117], v1 offset:0x600
	ds_read_b64_tr_b16 v[118:119], v1 offset:0xe00
	ds_read_b64_tr_b16 v[120:121], v1 offset:0x1600
	ds_read_b64_tr_b16 v[122:123], v1 offset:0x1e00
	ds_read_b64_tr_b16 v[124:125], v1 offset:0x2600
	ds_read_b64_tr_b16 v[126:127], v1 offset:0x2e00
	ds_read_b64_tr_b16 v[210:211], v1 offset:0x3600
	ds_read_b64_tr_b16 v[212:213], v1 offset:0x3e00
	s_waitcnt lgkmcnt(8)
	v_mfma_f32_32x32x16_bf16 v[32:47], v[96:99], v[100:103], v[32:47]
	v_mfma_f32_32x32x16_bf16 v[32:47], v[10:13], v[104:107], v[32:47]
	v_mfma_f32_32x32x16_bf16 v[32:47], v[6:9], v[108:111], v[32:47]
	v_mfma_f32_32x32x16_bf16 v[32:47], v[2:5], v[112:115], v[32:47]
	s_waitcnt lgkmcnt(0)
	s_lshl_b32 s99, s0, 13
	v_mfma_f32_32x32x16_bf16 v[16:31], v[96:99], v[116:119], v[16:31]
	v_add_u32_e32 v252, s99, v204
	v_add_u32_e32 v234, s99, v205
	ds_read_b128 v[236:239], v252
	ds_read_b128 v[240:243], v252 offset:4096
	v_mfma_f32_32x32x16_bf16 v[16:31], v[10:13], v[120:123], v[16:31]
	v_add_u32_e32 v235, s99, v206
	v_add_u32_e32 v254, s99, v207
	ds_read_b128 v[244:247], v234
	ds_read_b128 v[248:251], v234 offset:4096
	v_mfma_f32_32x32x16_bf16 v[16:31], v[6:9], v[124:127], v[16:31]
	ds_read_b128 v[216:219], v235
	ds_read_b128 v[220:223], v235 offset:4096
	ds_read_b128 v[224:227], v254
	ds_read_b128 v[228:231], v254 offset:4096
	v_mfma_f32_32x32x16_bf16 v[16:31], v[2:5], v[210:213], v[16:31]
	s_add_i32 s8, s8, 1
	s_add_u32 s6, s6, 0xc0000
	s_addc_u32 s7, s7, 0
	s_cmp_eq_u32 s8, s66
	s_cbranch_scc1 .LBB0_395
	s_mov_b32 s33, s0
	v_mov_b32_e32 v210, v14
	s_branch .LBB0_375

; #define SBAR() __builtin_amdgcn_sched_barrier(0)
; #define KRD(dst, addr, OFF) asm volatile("ds_read_b128 %0, %1 offset:" #OFF : "=&v"(dst) : "v"(addr) : "memory")
; __device__ __forceinline__ void diff_unit(const bf16_t* __restrict__ proj, bf16_t* __restrict__ mix, float* __restrict__ o1s, const float* __restrict__ g_sub, float lam,
;                                           int rowbase, int T, int h, int qb, char* lds, int widk) {
;     ...
;             { const int kb = bsl * DF_KSZ; bf16x8 k0, k1, k2, k3, k4, k5, k6, k7; const int a0 = ka[0] + kb, a1 = ka[1] + kb, a2 = ka[2] + kb, a3 = ka[3] + kb;
;               KRD(k0, a0, 0); KRD(k1, a0, 4096); KRD(k2, a1, 0); KRD(k3, a1, 4096); KRD(k4, a2, 0); KRD(k5, a2, 4096); KRD(k6, a3, 0); KRD(k7, a3, 4096);
;               asm volatile("s_waitcnt lgkmcnt(6)" ::: "memory"); SBAR();
;               asm volatile("v_mfma_f32_32x32x16_bf16 %0, %1, %2, %3" : "=&v"(p0) : "v"(k0), "v"(qr[0]), "v"(negm));
;               asm volatile("v_mfma_f32_32x32x16_bf16 %0, %1, %2, %3" : "=&v"(p1) : "v"(k1), "v"(qr[0]), "v"(negm)); SBAR();
;               asm volatile("s_waitcnt lgkmcnt(4)" ::: "memory"); SBAR();
;               p0 = __builtin_amdgcn_mfma_f32_32x32x16_bf16(k2, qr[1], p0, 0, 0, 0); p1 = __builtin_amdgcn_mfma_f32_32x32x16_bf16(k3, qr[1], p1, 0, 0, 0); SBAR();
;               asm volatile("s_waitcnt lgkmcnt(2)" ::: "memory"); SBAR();
;               p0 = __builtin_amdgcn_mfma_f32_32x32x16_bf16(k4, qr[2], p0, 0, 0, 0); p1 = __builtin_amdgcn_mfma_f32_32x32x16_bf16(k5, qr[2], p1, 0, 0, 0); SBAR();
;               asm volatile("s_waitcnt lgkmcnt(0)" ::: "memory"); SBAR();
;               p0 = __builtin_amdgcn_mfma_f32_32x32x16_bf16(k6, qr[3], p0, 0, 0, 0); p1 = __builtin_amdgcn_mfma_f32_32x32x16_bf16(k7, qr[3], p1, 0, 0, 0); SBAR(); }
.Ldf_fallback:
	s_lshl_b32 s98, s33, 13
	v_add_u32_e32 v252, s98, v204
	v_add_u32_e32 v234, s98, v205
	v_add_u32_e32 v235, s98, v206
	v_add_u32_e32 v254, s98, v207
	ds_read_b128 v[236:239], v252
	ds_read_b128 v[240:243], v252 offset:4096
	ds_read_b128 v[244:247], v234
	ds_read_b128 v[248:251], v234 offset:4096
	ds_read_b128 v[216:219], v235
	ds_read_b128 v[220:223], v235 offset:4096
	ds_read_b128 v[224:227], v254
	ds_read_b128 v[228:231], v254 offset:4096
	s_waitcnt lgkmcnt(0)
	v_mfma_f32_32x32x16_bf16 v[112:127], v[236:239], v[128:131], v[80:95]
	v_mfma_f32_32x32x16_bf16 v[96:111], v[240:243], v[128:131], v[80:95]
	v_mfma_f32_32x32x16_bf16 v[112:127], v[244:247], v[132:135], v[112:127]
	v_mfma_f32_32x32x16_bf16 v[96:111], v[248:251], v[132:135], v[96:111]
	v_mfma_f32_32x32x16_bf16 v[112:127], v[216:219], v[136:139], v[112:127]
	v_mfma_f32_32x32x16_bf16 v[96:111], v[220:223], v[136:139], v[96:111]
	v_mfma_f32_32x32x16_bf16 v[112:127], v[224:227], v[140:143], v[112:127]
	v_mfma_f32_32x32x16_bf16 v[96:111], v[228:231], v[140:143], v[96:111]
	s_nop 11
	s_branch .Ldf_slow

; __global__ void __launch_bounds__(NTHREADS, 2) fwd_kernel(Args a) {
	.amdhsa_kernel _Z10fwd_kernel4Args
		.amdhsa_group_segment_fixed_size 0
		.amdhsa_private_segment_fixed_size 0
		.amdhsa_kernarg_size 456
		.amdhsa_user_sgpr_count 2
		.amdhsa_user_sgpr_dispatch_ptr 0
		.amdhsa_user_sgpr_queue_ptr 0
		.amdhsa_user_sgpr_kernarg_segment_ptr 1
		.amdhsa_user_sgpr_dispatch_id 0
		.amdhsa_user_sgpr_kernarg_preload_length 0
		.amdhsa_user_sgpr_kernarg_preload_offset 0
		.amdhsa_user_sgpr_private_segment_size 0
		.amdhsa_uses_dynamic_stack 0
		.amdhsa_enable_private_segment 0
		.amdhsa_system_sgpr_workgroup_id_x 1
		.amdhsa_system_sgpr_workgroup_id_y 0
		.amdhsa_system_sgpr_workgroup_id_z 0
		.amdhsa_system_sgpr_workgroup_info 0
		.amdhsa_system_vgpr_workitem_id 2
		.amdhsa_next_free_vgpr 256
		.amdhsa_next_free_sgpr 100
		.amdhsa_accum_offset 256
		.amdhsa_reserve_vcc 1
		.amdhsa_float_round_mode_32 0
		.amdhsa_float_round_mode_16_64 0
		.amdhsa_float_denorm_mode_32 3
		.amdhsa_float_denorm_mode_16_64 3
		.amdhsa_dx10_clamp 1
		.amdhsa_ieee_mode 1
		.amdhsa_fp16_overflow 0
		.amdhsa_tg_split 0
		.amdhsa_exception_fp_ieee_invalid_op 0
		.amdhsa_exception_fp_denorm_src 0
		.amdhsa_exception_fp_ieee_div_zero 0
		.amdhsa_exception_fp_ieee_overflow 0
		.amdhsa_exception_fp_ieee_underflow 0
		.amdhsa_exception_fp_ieee_inexact 0
		.amdhsa_exception_int_div_zero 0
	.end_amdhsa_kernel

; __global__ void __launch_bounds__(NTHREADS, 2) fwd_kernel(Args a) {
amdhsa.kernels:
  - .agpr_count:     0
    .args:
      - .offset:         0
        .size:           200
        .value_kind:     by_value
      - .offset:         200
        .size:           4
        .value_kind:     hidden_block_count_x
      - .offset:         204
        .size:           4
        .value_kind:     hidden_block_count_y
      - .offset:         208
        .size:           4
        .value_kind:     hidden_block_count_z
      - .offset:         212
        .size:           2
        .value_kind:     hidden_group_size_x
      - .offset:         214
        .size:           2
        .value_kind:     hidden_group_size_y
      - .offset:         216
        .size:           2
        .value_kind:     hidden_group_size_z
      - .offset:         218
        .size:           2
        .value_kind:     hidden_remainder_x
      - .offset:         220
        .size:           2
        .value_kind:     hidden_remainder_y
      - .offset:         222
        .size:           2
        .value_kind:     hidden_remainder_z
      - .offset:         240
        .size:           8
        .value_kind:     hidden_global_offset_x
      - .offset:         248
        .size:           8
        .value_kind:     hidden_global_offset_y
      - .offset:         256
        .size:           8
        .value_kind:     hidden_global_offset_z
      - .offset:         264
        .size:           2
        .value_kind:     hidden_grid_dims
      - .offset:         288
        .size:           8
        .value_kind:     hidden_multigrid_sync_arg
      - .offset:         320
        .size:           4
        .value_kind:     hidden_dynamic_lds_size
    .group_segment_fixed_size: 0
    .kernarg_segment_align: 8
    .kernarg_segment_size: 456
    .language:       OpenCL C
    .language_version:
      - 2
      - 0
    .max_flat_workgroup_size: 512
    .name:           _Z10fwd_kernel4Args
    .private_segment_fixed_size: 0
    .sgpr_count:     106
    .sgpr_spill_count: 17
    .symbol:         _Z10fwd_kernel4Args.kd
    .uniform_work_group_size: 1
    .uses_dynamic_stack: false
    .vgpr_count:     256
    .vgpr_spill_count: 0
    .wavefront_size: 64
